# diff-attention loop: running-max-unchanged path falls straight through; rescale and subtract blocks moved out of line (4 fewer taken branches per trip)
# speedup vs baseline: 1.0093x; 1.0005x over previous
.LBB0_215:
	s_add_i32 s6, s5, 0x4000
	s_and_b32 s6, s6, 0xc000
	s_add_i32 s7, s15, s6
	s_add_i32 s6, s16, s6
	s_mov_b32 s98, s7
	s_mov_b32 s99, s6
	s_waitcnt vmcnt(4)
	s_barrier
	s_add_u32 s100, s74, s36
	s_addc_u32 s101, s75, s37
	s_add_u32 s34, s74, s58
	s_addc_u32 s35, s75, s59
	s_add_i32 s6, s5, 0xffff8000
	s_and_b32 s6, s6, 0x8000
	s_add_i32 s7, s6, 0
	ds_read_b128 v[68:71], v208 offset:16384
	ds_read_b128 v[72:75], v208 offset:24576
	ds_read_b128 v[76:79], v209 offset:16384
	ds_read_b128 v[162:165], v209 offset:24576
	v_max3_f32 v240, v98, v82, v99
	v_max3_f32 v66, v83, v100, v84
	s_waitcnt lgkmcnt(0)
	v_mfma_f32_32x32x16_bf16 v[146:161], v[68:71], v[190:193], v[114:129]
	v_max3_f32 v240, v240, v101, v85
	v_max3_f32 v66, v66, v102, v86
	v_mfma_f32_32x32x16_bf16 v[130:145], v[72:75], v[190:193], v[114:129]
	s_mov_b32 m0, s98
	s_nop 0
	global_load_lds_dwordx4 v206, s[100:101]
	ds_read_b128 v[68:71], v210 offset:16384
	ds_read_b128 v[72:75], v210 offset:24576
	v_max3_f32 v240, v240, v103, v87
	v_max3_f32 v66, v66, v104, v88
	v_mfma_f32_32x32x16_bf16 v[146:161], v[76:79], v[186:189], v[146:161]
	ds_read_b128 v[76:79], v211 offset:16384
	ds_read_b128 v[166:169], v211 offset:24576
	v_max3_f32 v240, v240, v105, v89
	v_max3_f32 v66, v66, v106, v90
	v_mfma_f32_32x32x16_bf16 v[130:145], v[162:165], v[186:189], v[130:145]
	s_waitcnt lgkmcnt(0)
	v_max3_f32 v240, v240, v107, v91
	v_max3_f32 v66, v66, v108, v92
	v_mfma_f32_32x32x16_bf16 v[146:161], v[68:71], v[182:185], v[146:161]
	v_max3_f32 v240, v240, v109, v93
	v_max3_f32 v66, v66, v110, v94
	v_mfma_f32_32x32x16_bf16 v[130:145], v[72:75], v[182:185], v[130:145]
	s_mov_b32 m0, s99
	s_nop 0
	global_load_lds_dwordx4 v80, s[34:35]
	v_max3_f32 v240, v240, v111, v95
	v_max3_f32 v66, v66, v112, v96
	v_mfma_f32_32x32x16_bf16 v[146:161], v[76:79], v[178:181], v[146:161]
	v_max3_f32 v240, v240, v113, v97
	v_max3_f32 v240, v240, v66, v66
	v_mfma_f32_32x32x16_bf16 v[130:145], v[166:169], v[178:181], v[130:145]
	s_add_i32 s7, s7, 0x10000
	v_add_u32_e32 v212, s7, v227
	ds_read_b128 v[194:197], v212
	ds_read_b128 v[76:79], v212 offset:4096
	ds_read_b128 v[72:75], v212 offset:8192
	ds_read_b128 v[68:71], v212 offset:12288
	v_mov_b32_e32 v66, v240
	s_nop 1
	v_permlane32_swap_b32_e32 v240, v66
	v_max3_f32 v198, v240, v66, v66
	s_nop 0
	v_pk_add_f32 v[162:163], v[200:201], v[198:199]
	s_nop 0
	v_cmp_gt_f32_e32 vcc, v162, v163
	s_nop 1
	v_cndmask_b32_e32 v0, v201, v162, vcc
	v_cmp_gt_f32_e32 vcc, v0, v201
	s_cbranch_vccnz .Lda_rescale_a
	v_mov_b64_e32 v[176:177], v[128:129]
	v_mov_b64_e32 v[174:175], v[126:127]
	v_mov_b64_e32 v[172:173], v[124:125]
	v_mov_b64_e32 v[170:171], v[122:123]
	v_mov_b64_e32 v[168:169], v[120:121]
	v_mov_b64_e32 v[166:167], v[118:119]
	v_mov_b64_e32 v[164:165], v[116:117]
	v_mov_b64_e32 v[162:163], v[114:115]
	v_mov_b32_e32 v66, v114
	v_sub_f32_e32 v0, v0, v200
	v_cmp_neq_f32_e32 vcc, 0, v0
	s_cbranch_vccnz .LBB0_217

.LBB0_220:
	s_bitset1_b32 s6, 14
	s_and_b32 s7, s5, 0x8000
	s_add_i32 s7, s7, 0
	v_xor_b32_e32 v208, 0x8000, v208
	v_xor_b32_e32 v209, 0x8000, v209
	ds_read_b128 v[68:71], v208
	ds_read_b128 v[72:75], v208 offset:8192
	ds_read_b128 v[76:79], v209
	ds_read_b128 v[194:197], v209 offset:8192
	s_waitcnt lgkmcnt(0)
	v_mfma_f32_32x32x16_bf16 v[98:113], v[68:71], v[190:193], v[162:177]
	v_mfma_f32_32x32x16_bf16 v[82:97], v[72:75], v[190:193], v[162:177]
	v_xor_b32_e32 v210, 0x8000, v210
	ds_read_b128 v[68:71], v210
	ds_read_b128 v[72:75], v210 offset:8192
	s_nop 3
	v_xor_b32_e32 v211, 0x8000, v211
	v_mfma_f32_32x32x16_bf16 v[98:113], v[76:79], v[186:189], v[98:113]
	ds_read_b128 v[76:79], v211
	ds_read_b128 v[164:167], v211 offset:8192
	v_max3_f32 v163, v146, v130, v147
	v_max3_f32 v168, v131, v148, v132
	v_mfma_f32_32x32x16_bf16 v[82:97], v[194:197], v[186:189], v[82:97]
	s_waitcnt lgkmcnt(0)
	v_max3_f32 v163, v163, v149, v133
	v_max3_f32 v168, v168, v150, v134
	v_mfma_f32_32x32x16_bf16 v[98:113], v[68:71], v[182:185], v[98:113]
	v_max3_f32 v163, v163, v151, v135
	v_max3_f32 v168, v168, v152, v136
	v_mfma_f32_32x32x16_bf16 v[82:97], v[72:75], v[182:185], v[82:97]
	v_max3_f32 v163, v163, v153, v137
	v_max3_f32 v168, v168, v154, v138
	v_max3_f32 v163, v163, v155, v139
	v_max3_f32 v168, v168, v156, v140
	v_mfma_f32_32x32x16_bf16 v[98:113], v[76:79], v[178:181], v[98:113]
	v_max3_f32 v163, v163, v157, v141
	v_max3_f32 v168, v168, v158, v142
	v_max3_f32 v163, v163, v159, v143
	v_max3_f32 v168, v168, v160, v144
	v_mfma_f32_32x32x16_bf16 v[82:97], v[164:167], v[178:181], v[82:97]
	ds_read_b128 v[164:167], v212 offset:16384
	ds_read_b128 v[76:79], v212 offset:20480
	ds_read_b128 v[72:75], v212 offset:24576
	ds_read_b128 v[68:71], v212 offset:28672
	v_max3_f32 v163, v163, v161, v145
	v_max3_f32 v163, v163, v168, v168
	v_mov_b32_e32 v168, v163
	s_nop 1
	v_permlane32_swap_b32_e32 v163, v168
	v_max3_f32 v163, v163, v168, v168
	v_add_f32_e32 v168, 0x41000000, v201
	v_sub_f32_e32 v163, v163, v114
	v_cmp_gt_f32_e32 vcc, v163, v168
	s_nop 1
	v_cndmask_b32_e32 v163, v201, v163, vcc
	v_cmp_gt_f32_e32 vcc, v163, v201
	s_cbranch_vccnz .Lda_rescale_b
.LBB0_222:
	v_add_f32_e32 v114, v114, v163
	v_cmp_neq_f32_e32 vcc, 0, v114
	s_cbranch_vccnz .Lda_sub_b

.Lda_rescale_a:
	v_sub_f32_e32 v66, v201, v0
	v_exp_f32_e32 v66, v66
	v_xor_b32_e32 v162, 0x80000000, v0
	v_mov_b32_e32 v163, v162
	v_mov_b32_e32 v164, v162
	v_pk_mul_f32 v[64:65], v[64:65], v[66:67] op_sel_hi:[1,0]
	v_pk_mul_f32 v[62:63], v[62:63], v[66:67] op_sel_hi:[1,0]
	v_pk_mul_f32 v[60:61], v[60:61], v[66:67] op_sel_hi:[1,0]
	v_pk_mul_f32 v[58:59], v[58:59], v[66:67] op_sel_hi:[1,0]
	v_pk_mul_f32 v[56:57], v[56:57], v[66:67] op_sel_hi:[1,0]
	v_pk_mul_f32 v[54:55], v[54:55], v[66:67] op_sel_hi:[1,0]
	v_pk_mul_f32 v[52:53], v[52:53], v[66:67] op_sel_hi:[1,0]
	v_pk_mul_f32 v[50:51], v[50:51], v[66:67] op_sel_hi:[1,0]
	v_pk_mul_f32 v[48:49], v[48:49], v[66:67] op_sel_hi:[1,0]
	v_pk_mul_f32 v[46:47], v[46:47], v[66:67] op_sel_hi:[1,0]
	v_pk_mul_f32 v[44:45], v[44:45], v[66:67] op_sel_hi:[1,0]
	v_pk_mul_f32 v[42:43], v[42:43], v[66:67] op_sel_hi:[1,0]
	v_pk_mul_f32 v[40:41], v[40:41], v[66:67] op_sel_hi:[1,0]
	v_pk_mul_f32 v[38:39], v[38:39], v[66:67] op_sel_hi:[1,0]
	v_pk_mul_f32 v[36:37], v[36:37], v[66:67] op_sel_hi:[1,0]
	v_pk_mul_f32 v[34:35], v[34:35], v[66:67] op_sel_hi:[1,0]
	v_pk_mul_f32 v[32:33], v[32:33], v[66:67] op_sel_hi:[1,0]
	v_pk_mul_f32 v[30:31], v[30:31], v[66:67] op_sel_hi:[1,0]
	v_pk_mul_f32 v[28:29], v[28:29], v[66:67] op_sel_hi:[1,0]
	v_pk_mul_f32 v[26:27], v[26:27], v[66:67] op_sel_hi:[1,0]
	v_pk_mul_f32 v[24:25], v[24:25], v[66:67] op_sel_hi:[1,0]
	v_pk_mul_f32 v[22:23], v[22:23], v[66:67] op_sel_hi:[1,0]
	v_pk_mul_f32 v[20:21], v[20:21], v[66:67] op_sel_hi:[1,0]
	v_pk_mul_f32 v[18:19], v[18:19], v[66:67] op_sel_hi:[1,0]
	v_pk_mul_f32 v[16:17], v[16:17], v[66:67] op_sel_hi:[1,0]
	v_pk_mul_f32 v[14:15], v[14:15], v[66:67] op_sel_hi:[1,0]
	v_pk_mul_f32 v[12:13], v[12:13], v[66:67] op_sel_hi:[1,0]
	v_pk_mul_f32 v[10:11], v[10:11], v[66:67] op_sel_hi:[1,0]
	v_pk_mul_f32 v[8:9], v[8:9], v[66:67] op_sel_hi:[1,0]
	v_pk_mul_f32 v[6:7], v[6:7], v[66:67] op_sel_hi:[1,0]
	v_pk_mul_f32 v[4:5], v[4:5], v[66:67] op_sel_hi:[1,0]
	v_pk_mul_f32 v[2:3], v[2:3], v[66:67] op_sel_hi:[1,0]
	v_mul_f32_e32 v232, v232, v66
	v_mov_b32_e32 v165, v162
	v_mov_b32_e32 v166, v162
	v_mov_b32_e32 v167, v162
	v_mov_b32_e32 v168, v162
	v_mov_b32_e32 v169, v162
	v_mov_b32_e32 v170, v162
	v_mov_b32_e32 v171, v162
	v_mov_b32_e32 v172, v162
	v_mov_b32_e32 v173, v162
	v_mov_b32_e32 v174, v162
	v_mov_b32_e32 v175, v162
	v_mov_b32_e32 v176, v162
	v_mov_b32_e32 v177, v162
	v_mov_b32_e32 v201, v0
	v_mov_b32_e32 v66, v162
	v_mov_b32_e32 v115, v162
	v_mov_b32_e32 v116, v162
	v_mov_b32_e32 v117, v162
	v_mov_b32_e32 v118, v162
	v_mov_b32_e32 v119, v162
	v_mov_b32_e32 v120, v162
	v_mov_b32_e32 v121, v162
	v_mov_b32_e32 v122, v162
	v_mov_b32_e32 v123, v162
	v_mov_b32_e32 v124, v162
	v_mov_b32_e32 v125, v162
	v_mov_b32_e32 v126, v162
	v_mov_b32_e32 v127, v162
	v_mov_b32_e32 v128, v162
	v_mov_b32_e32 v129, v162
	v_sub_f32_e32 v0, v0, v200
	v_cmp_neq_f32_e32 vcc, 0, v0
	s_cbranch_vccz .LBB0_218
.LBB0_217:
	v_sub_f32_e32 v101, v101, v0
	v_sub_f32_e32 v102, v102, v0
	v_sub_f32_e32 v103, v103, v0
	v_sub_f32_e32 v104, v104, v0
	v_sub_f32_e32 v105, v105, v0
	v_sub_f32_e32 v106, v106, v0
	v_sub_f32_e32 v107, v107, v0
	v_sub_f32_e32 v108, v108, v0
	v_sub_f32_e32 v109, v109, v0
	v_sub_f32_e32 v110, v110, v0
	v_sub_f32_e32 v111, v111, v0
	v_sub_f32_e32 v112, v112, v0
	v_sub_f32_e32 v98, v98, v0
	v_sub_f32_e32 v99, v99, v0
	v_sub_f32_e32 v100, v100, v0
	v_sub_f32_e32 v113, v113, v0
	v_sub_f32_e32 v85, v85, v0
	v_sub_f32_e32 v86, v86, v0
	v_sub_f32_e32 v87, v87, v0
	v_sub_f32_e32 v88, v88, v0
	v_sub_f32_e32 v89, v89, v0
	v_sub_f32_e32 v90, v90, v0
	v_sub_f32_e32 v91, v91, v0
	v_sub_f32_e32 v92, v92, v0
	v_sub_f32_e32 v93, v93, v0
	v_sub_f32_e32 v94, v94, v0
	v_sub_f32_e32 v95, v95, v0
	v_sub_f32_e32 v96, v96, v0
	v_sub_f32_e32 v82, v82, v0
	v_sub_f32_e32 v83, v83, v0
	v_sub_f32_e32 v84, v84, v0
	v_sub_f32_e32 v97, v97, v0
	s_branch .LBB0_218
.Lda_rescale_b:
	v_sub_f32_e32 v66, v201, v163
	v_exp_f32_e32 v116, v66
	v_xor_b32_e32 v66, 0x80000000, v163
	v_mov_b32_e32 v201, v163
	v_mov_b32_e32 v115, v66
	v_pk_mul_f32 v[64:65], v[64:65], v[116:117] op_sel_hi:[1,0]
	v_pk_mul_f32 v[62:63], v[62:63], v[116:117] op_sel_hi:[1,0]
	v_pk_mul_f32 v[60:61], v[60:61], v[116:117] op_sel_hi:[1,0]
	v_pk_mul_f32 v[58:59], v[58:59], v[116:117] op_sel_hi:[1,0]
	v_pk_mul_f32 v[56:57], v[56:57], v[116:117] op_sel_hi:[1,0]
	v_pk_mul_f32 v[54:55], v[54:55], v[116:117] op_sel_hi:[1,0]
	v_pk_mul_f32 v[52:53], v[52:53], v[116:117] op_sel_hi:[1,0]
	v_pk_mul_f32 v[50:51], v[50:51], v[116:117] op_sel_hi:[1,0]
	v_pk_mul_f32 v[48:49], v[48:49], v[116:117] op_sel_hi:[1,0]
	v_pk_mul_f32 v[46:47], v[46:47], v[116:117] op_sel_hi:[1,0]
	v_pk_mul_f32 v[44:45], v[44:45], v[116:117] op_sel_hi:[1,0]
	v_pk_mul_f32 v[42:43], v[42:43], v[116:117] op_sel_hi:[1,0]
	v_pk_mul_f32 v[40:41], v[40:41], v[116:117] op_sel_hi:[1,0]
	v_pk_mul_f32 v[38:39], v[38:39], v[116:117] op_sel_hi:[1,0]
	v_pk_mul_f32 v[36:37], v[36:37], v[116:117] op_sel_hi:[1,0]
	v_pk_mul_f32 v[34:35], v[34:35], v[116:117] op_sel_hi:[1,0]
	v_pk_mul_f32 v[32:33], v[32:33], v[116:117] op_sel_hi:[1,0]
	v_pk_mul_f32 v[30:31], v[30:31], v[116:117] op_sel_hi:[1,0]
	v_pk_mul_f32 v[28:29], v[28:29], v[116:117] op_sel_hi:[1,0]
	v_pk_mul_f32 v[26:27], v[26:27], v[116:117] op_sel_hi:[1,0]
	v_pk_mul_f32 v[24:25], v[24:25], v[116:117] op_sel_hi:[1,0]
	v_pk_mul_f32 v[22:23], v[22:23], v[116:117] op_sel_hi:[1,0]
	v_pk_mul_f32 v[20:21], v[20:21], v[116:117] op_sel_hi:[1,0]
	v_pk_mul_f32 v[18:19], v[18:19], v[116:117] op_sel_hi:[1,0]
	v_pk_mul_f32 v[16:17], v[16:17], v[116:117] op_sel_hi:[1,0]
	v_pk_mul_f32 v[14:15], v[14:15], v[116:117] op_sel_hi:[1,0]
	v_pk_mul_f32 v[12:13], v[12:13], v[116:117] op_sel_hi:[1,0]
	v_pk_mul_f32 v[10:11], v[10:11], v[116:117] op_sel_hi:[1,0]
	v_pk_mul_f32 v[8:9], v[8:9], v[116:117] op_sel_hi:[1,0]
	v_pk_mul_f32 v[6:7], v[6:7], v[116:117] op_sel_hi:[1,0]
	v_pk_mul_f32 v[4:5], v[4:5], v[116:117] op_sel_hi:[1,0]
	v_pk_mul_f32 v[2:3], v[2:3], v[116:117] op_sel_hi:[1,0]
	v_mul_f32_e32 v0, v0, v116
	v_mov_b32_e32 v116, v66
	v_mov_b32_e32 v117, v66
	v_mov_b32_e32 v118, v66
	v_mov_b32_e32 v119, v66
	v_mov_b32_e32 v120, v66
	v_mov_b32_e32 v121, v66
	v_mov_b32_e32 v122, v66
	v_mov_b32_e32 v123, v66
	v_mov_b32_e32 v124, v66
	v_mov_b32_e32 v125, v66
	v_mov_b32_e32 v126, v66
	v_mov_b32_e32 v127, v66
	v_mov_b32_e32 v128, v66
	v_mov_b32_e32 v129, v66
	s_branch .LBB0_222
.Lda_sub_b:
	v_sub_f32_e32 v149, v149, v114
	v_sub_f32_e32 v150, v150, v114
	v_sub_f32_e32 v151, v151, v114
	v_sub_f32_e32 v152, v152, v114
	v_sub_f32_e32 v153, v153, v114
	v_sub_f32_e32 v154, v154, v114
	v_sub_f32_e32 v155, v155, v114
	v_sub_f32_e32 v156, v156, v114
	v_sub_f32_e32 v157, v157, v114
	v_sub_f32_e32 v158, v158, v114
	v_sub_f32_e32 v159, v159, v114
	v_sub_f32_e32 v160, v160, v114
	v_sub_f32_e32 v146, v146, v114
	v_sub_f32_e32 v147, v147, v114
	v_sub_f32_e32 v148, v148, v114
	v_sub_f32_e32 v161, v161, v114
	v_sub_f32_e32 v133, v133, v114
	v_sub_f32_e32 v134, v134, v114
	v_sub_f32_e32 v135, v135, v114
	v_sub_f32_e32 v136, v136, v114
	v_sub_f32_e32 v137, v137, v114
	v_sub_f32_e32 v138, v138, v114
	v_sub_f32_e32 v139, v139, v114
	v_sub_f32_e32 v140, v140, v114
	v_sub_f32_e32 v141, v141, v114
	v_sub_f32_e32 v142, v142, v114
	v_sub_f32_e32 v143, v143, v114
	v_sub_f32_e32 v144, v144, v114
	v_sub_f32_e32 v130, v130, v114
	v_sub_f32_e32 v131, v131, v114
	v_sub_f32_e32 v132, v132, v114
	v_sub_f32_e32 v145, v145, v114
	s_branch .LBB0_224
